# attention: QK^T MFMA block at s_setprio 1 (in addition to the P.V block at 2)
# speedup vs baseline: 1.0182x; 1.0068x over previous
.LBB0_256:
	s_setprio 0
	s_add_i32 s17, s78, s12
	s_add_i32 s17, s17, -4
	v_mov_b32_e32 v211, s17
	ds_read_b32 v210, v211
	s_add_i32 s17, s16, 1
	s_cmp_lg_u32 s16, 2
	s_cselect_b32 s17, s17, 0
	s_mul_i32 s17, s17, 0x4400
	v_add_u32_e32 v178, s17, v193
	ds_read_b128 v[246:249], v178
	ds_read_b128 v[250:253], v178 offset:32
	ds_read_b128 v[200:203], v178 offset:64
	ds_read_b128 v[204:207], v178 offset:96
	ds_read_b128 v[100:103], v178 offset:8704
	ds_read_b128 v[104:107], v178 offset:8736
	s_add_i32 s17, s12, 0xfffe4404
	s_and_b32 s17, s17, 4
	s_xor_b32 s40, s17, 4
	s_lshl_b32 s18, s40, 2
	s_add_i32 s18, s18, 0x1c040
	v_mov_b32_e32 v176, s18
	s_lshl_b32 s17, s17, 2
	s_add_i32 s17, s17, 0x1c060
	v_mov_b32_e32 v177, s17
	s_waitcnt lgkmcnt(7)
	s_barrier
	ds_read_b128 v[168:171], v176
	ds_read_b128 v[172:175], v177
	s_setprio 1
	s_waitcnt lgkmcnt(7)
	v_mfma_f32_32x32x16_bf16 v[80:95], v[246:249], v[108:111], v[214:229]
	ds_read_b128 v[246:249], v178 offset:8768
	s_waitcnt lgkmcnt(7)
	v_mfma_f32_32x32x16_bf16 v[80:95], v[250:253], v[112:115], v[80:95]
	ds_read_b128 v[250:253], v178 offset:8800
	s_waitcnt lgkmcnt(7)
	v_mfma_f32_32x32x16_bf16 v[80:95], v[200:203], v[116:119], v[80:95]
	s_waitcnt lgkmcnt(6)
	v_mfma_f32_32x32x16_bf16 v[80:95], v[204:207], v[120:123], v[80:95]
	s_waitcnt lgkmcnt(5)
	v_mfma_f32_32x32x16_bf16 v[64:79], v[100:103], v[108:111], v[230:245]
	s_waitcnt lgkmcnt(4)
	v_mfma_f32_32x32x16_bf16 v[64:79], v[104:107], v[112:115], v[64:79]
	s_waitcnt lgkmcnt(1)
	v_mfma_f32_32x32x16_bf16 v[64:79], v[246:249], v[116:119], v[64:79]
	s_waitcnt lgkmcnt(0)
	v_mfma_f32_32x32x16_bf16 v[64:79], v[250:253], v[120:123], v[64:79]
	s_setprio 0
	s_waitcnt lgkmcnt(0)
	v_and_b32_e32 v168, v168, v169
	v_and_b32_e32 v168, v168, v170
	v_and_b32_e32 v168, v168, v171
	v_and_b32_e32 v168, v168, v172
	v_and_b32_e32 v168, v168, v173
	v_and_b32_e32 v168, v168, v174
	v_and_b32_e32 v168, v168, v175
	v_cmp_ne_u32_e32 vcc, 0, v168
	s_cbranch_vccz .LBB0_260
	s_branch .LBB0_262
